# w_in_odd weight transposes moved from scan0 phase to the 64 tile-less WGs of the out0 GEMM phase
# speedup vs baseline: 1.0288x; 1.0083x over previous
.LBB0_890:
	s_cmp_gt_i32 s2, 63
	s_cselect_b64 s[0:1], -1, 0
	s_sub_i32 s3, s2, 32
	s_add_u32 s14, s24, 0xa10000
	s_addc_u32 s15, s25, 0
	v_readlane_b32 s4, v254, 11
	s_add_u32 s8, s24, 0x1210000
	v_readlane_b32 s5, v254, 12
	s_addc_u32 s9, s25, 0
	s_and_b64 s[0:1], s[0:1], s[4:5]
	s_cmpk_gt_u32 s2, 0xdf
	v_readlane_b32 s4, v254, 35
	s_cselect_b32 s10, s4, -1
	s_add_u32 s6, s24, 0x810000
	v_readlane_b32 s94, v254, 22
	s_addc_u32 s7, s25, 0
	v_readlane_b32 s95, v254, 23
	s_and_b64 s[4:5], s[94:95], exec
	v_readlane_b32 s4, v254, 26
	v_readlane_b32 s5, v254, 27
	s_cselect_b32 s3, s3, s10
	s_and_b64 s[4:5], s[4:5], exec
	s_cselect_b32 s3, s3, -1
	s_and_b64 s[0:1], s[0:1], exec
	v_readlane_b32 s90, v254, 13
	s_cselect_b32 s3, s3, s2
	v_readlane_b32 s91, v254, 14
	v_readlane_b32 s92, v254, 15
	s_cmp_lt_i32 s3, 0
	v_readlane_b32 s93, v254, 16
	v_readlane_b32 s91, v254, 17
	v_readlane_b32 s88, v254, 38
	v_readlane_b32 s89, v254, 39
	s_cbranch_scc1 .LBB0_935
	v_readlane_b32 s0, v254, 11
	v_readlane_b32 s1, v254, 12
	s_and_b64 s[0:1], s[0:1], exec
	s_cselect_b32 s10, 0xc0, s26
	s_lshl_b32 s11, s10, 1
	s_cmpk_gt_u32 s3, 0x1ff
	s_branch .LBB0_898

.LBB0_1070:
	s_barrier
	s_branch .LBB0_1071
.Lprep_in_odd:
	s_waitcnt vmcnt(0)
	s_add_i32 s0, s2, 0xffffff40
	s_lshl_b32 s42, s0, 1
	s_lshl_b32 s43, s0, 7
	s_add_u32 s46, s24, 0xa10000
	s_addc_u32 s47, s25, 0
	v_mov_b32_e32 v1, 0
	s_movk_i32 s17, 0xffc0
	s_mov_b32 s19, 0x80000
	s_movk_i32 s28, 0x104
	s_movk_i32 s29, 0x1000
	s_movk_i32 s35, 0x800
	s_branch .Lpi_loop
.Lpi_next:
	s_or_b64 exec, exec, s[0:1]
	s_addk_i32 s42, 0x80
	s_addk_i32 s43, 0x2000
	s_cmpk_gt_i32 s42, 0x3ff
	s_barrier
	s_cbranch_scc1 .LBB0_1071
.Lpi_loop:
	s_ashr_i32 s0, s42, 31
	s_lshr_b32 s0, s0, 26
	s_add_i32 s1, s42, s0
	s_waitcnt vmcnt(3)
	v_mov_b32_e32 v22, v224
	s_and_b32 s0, s1, 0xffffffc0
	s_lshl_b32 s1, s1, 6
	v_readlane_b32 s68, v254, 0
	v_lshlrev_b32_e32 v0, 4, v22
	s_and_b32 s1, s1, 0xfffff000
	v_and_b32_e32 v0, 0xf0, v0
	v_readlane_b32 s69, v254, 1
	s_sub_i32 s4, s43, s1
	v_ashrrev_i32_e32 v23, 4, v22
	v_lshl_add_u64 v[2:3], s[68:69], 0, v[0:1]
	s_ashr_i32 s5, s4, 31
	s_add_i32 s40, s42, 1
	s_waitcnt vmcnt(2)
	v_add_u32_e32 v4, s0, v23
	v_lshl_add_u64 v[6:7], s[4:5], 2, v[2:3]
	s_min_i32 s4, s40, 0x3ff
	v_ashrrev_i32_e32 v5, 31, v4
	s_ashr_i32 s5, s4, 31
	v_lshlrev_b64 v[4:5], 14, v[4:5]
	s_lshr_b32 s5, s5, 26
	v_lshl_add_u64 v[4:5], v[6:7], 0, v[4:5]
	s_add_i32 s5, s4, s5
	v_add_co_u32_e32 v10, vcc, s19, v4
	s_andn2_b32 s5, s5, 63
	s_nop 0
	v_addc_co_u32_e32 v11, vcc, 0, v5, vcc
	s_sub_i32 s4, s4, s5
	global_load_dwordx4 v[6:9], v[4:5], off nt
	s_nop 0
	global_load_dwordx4 v[10:13], v[10:11], off nt
	s_lshl_b32 s4, s4, 6
	v_add_u32_e32 v4, s5, v23
	s_ashr_i32 s5, s4, 31
	v_ashrrev_i32_e32 v5, 31, v4
	v_lshl_add_u64 v[2:3], s[4:5], 2, v[2:3]
	v_lshlrev_b64 v[4:5], 14, v[4:5]
	v_lshl_add_u64 v[2:3], v[2:3], 0, v[4:5]
	global_load_dwordx4 v[14:17], v[2:3], off nt
	v_add_co_u32_e32 v2, vcc, s19, v2
	v_mul_lo_u32 v4, v23, s28
	s_nop 0
	v_addc_co_u32_e32 v3, vcc, 0, v3, vcc
	global_load_dwordx4 v[18:21], v[2:3], off nt
	v_ashrrev_i32_e32 v3, 3, v22
	v_lshlrev_b32_e32 v5, 1, v3
	v_lshlrev_b32_e32 v2, 3, v22
	v_add3_u32 v0, 0, v0, v4
	v_and_b32_e32 v4, 62, v5
	v_subrev_u32_e32 v5, s1, v3
	v_and_b32_e32 v22, 56, v2
	v_lshl_add_u32 v2, v3, 2, 0
	v_lshrrev_b32_e32 v23, 5, v3
	v_add_u32_e32 v5, s43, v5
	v_mad_u32_u24 v2, v22, s28, v2
	v_add_u32_e32 v24, 0x2080, v0
	v_add_u32_e32 v25, 0x2088, v0
	v_add_u32_e32 v26, 0x4100, v0
	v_add_u32_e32 v27, 0x4108, v0
	v_add_u32_e32 v28, 0x6180, v0
	v_add_u32_e32 v29, 0x6188, v0
	v_and_or_b32 v4, v23, 1, v4
	v_cmp_gt_i32_e32 vcc, s29, v5
	s_waitcnt vmcnt(3)
	ds_write2_b32 v0, v6, v7 offset1:1
	ds_write2_b32 v0, v8, v9 offset0:2 offset1:3
	s_waitcnt vmcnt(2)
	ds_write2_b32 v24, v10, v11 offset1:1
	ds_write2_b32 v25, v12, v13 offset1:1
	s_waitcnt vmcnt(1)
	ds_write2_b32 v26, v14, v15 offset1:1
	ds_write2_b32 v27, v16, v17 offset1:1
	s_waitcnt vmcnt(0)
	ds_write2_b32 v28, v18, v19 offset1:1
	ds_write2_b32 v29, v20, v21 offset1:1
	v_lshlrev_b32_e32 v0, 1, v22
	s_waitcnt lgkmcnt(0)
	s_barrier
	s_and_saveexec_b64 s[4:5], vcc
	s_cbranch_execz .Lpi_896
	ds_read2_b32 v[6:7], v2 offset1:65
	ds_read2_b32 v[8:9], v2 offset0:130 offset1:195
	v_add_u32_e32 v12, 0x400, v2
	ds_read2_b32 v[10:11], v12 offset0:4 offset1:69
	ds_read2_b32 v[12:13], v12 offset0:134 offset1:199
	v_and_or_b32 v14, v5, s17, v4
	v_cmp_gt_i32_e32 vcc, s35, v5
	s_waitcnt lgkmcnt(3)
	v_cvt_pk_bf16_f32 v6, v6, v7
	s_waitcnt lgkmcnt(2)
	v_cvt_pk_bf16_f32 v7, v8, v9
	v_cndmask_b32_e32 v14, v5, v14, vcc
	v_ashrrev_i32_e32 v15, 31, v14
	s_waitcnt lgkmcnt(1)
	v_cvt_pk_bf16_f32 v8, v10, v11
	v_lshlrev_b64 v[10:11], 11, v[14:15]
	v_lshl_add_u64 v[10:11], s[46:47], 0, v[10:11]
	s_ashr_i32 s1, s0, 31
	v_lshl_add_u64 v[10:11], s[0:1], 1, v[10:11]
	s_waitcnt lgkmcnt(0)
	v_cvt_pk_bf16_f32 v9, v12, v13
	v_lshl_add_u64 v[10:11], v[10:11], 0, v[0:1]
	global_store_dwordx4 v[10:11], v[6:9], off
.Lpi_896:
	s_or_b64 exec, exec, s[4:5]
	s_ashr_i32 s0, s40, 31
	s_lshr_b32 s0, s0, 26
	s_add_i32 s4, s40, s0
	s_and_b32 s0, s4, 0x3ffffc0
	s_sub_i32 s0, s40, s0
	v_lshl_add_u32 v3, s0, 6, v3
	v_cmp_gt_i32_e32 vcc, s29, v3
	s_and_saveexec_b64 s[0:1], vcc
	s_cbranch_execz .Lpi_next
	v_add_u32_e32 v5, 0x4000, v2
	ds_read2_b32 v[6:7], v5 offset0:64 offset1:129
	v_add_u32_e32 v5, 0x4200, v2
	ds_read2_b32 v[8:9], v5 offset0:66 offset1:131
	v_add_u32_e32 v5, 0x4400, v2
	v_add_u32_e32 v2, 0x4600, v2
	ds_read2_b32 v[12:13], v2 offset0:70 offset1:135
	v_and_or_b32 v2, v3, s17, v4
	v_cmp_gt_i32_e32 vcc, s35, v3
	ds_read2_b32 v[10:11], v5 offset0:68 offset1:133
	s_ashr_i32 s4, s4, 6
	v_cndmask_b32_e32 v14, v3, v2, vcc
	v_ashrrev_i32_e32 v15, 31, v14
	s_lshl_b32 s4, s4, 6
	s_waitcnt lgkmcnt(3)
	v_cvt_pk_bf16_f32 v2, v6, v7
	v_lshlrev_b64 v[6:7], 11, v[14:15]
	v_lshl_add_u64 v[6:7], s[46:47], 0, v[6:7]
	s_ashr_i32 s5, s4, 31
	v_lshl_add_u64 v[6:7], s[4:5], 1, v[6:7]
	s_waitcnt lgkmcnt(2)
	v_cvt_pk_bf16_f32 v3, v8, v9
	s_waitcnt lgkmcnt(0)
	v_cvt_pk_bf16_f32 v4, v10, v11
	v_cvt_pk_bf16_f32 v5, v12, v13
	v_lshl_add_u64 v[6:7], v[6:7], 0, v[0:1]
	global_store_dwordx4 v[6:7], v[2:5], off
	s_branch .Lpi_next
